# code placement: 16 bytes of unreachable padding after the NA tile loop (shifts SWA + later GEMM loops), on pack_more
# baseline (speedup 1.0000x reference)
; #define LAS __attribute__((address_space(3)))
; template <int MODE> ...
;     ...
;         if (t >= act0 && t < act0 + actn) {
;         const LAS unsigned char* Sl = ring + ((t + base) % 3) * SLOT;
; #pragma unroll
;         for (int hf = 0; hf < NH; ++hf) {
;             if (MODE == 1) { const int ks = ktok0 + 64 * t + 32 * hf;
;                 if (ks + 31 < qtok0 - 128 || ks > qtok0 + 31 + 128) continue; }
;             bf16x8 kf[2][2][2];
; #pragma unroll
;             for (int jj = 0; jj < 2; ++jj)
; #pragma unroll
;                 for (int kt = 0; kt < 2; ++kt)
; #pragma unroll
;                     for (int ks = 0; ks < 2; ++ks) kf[jj][kt][ks] = *(const LAS bf16x8*)(Sl + kad[jj][ks] + (32 * hf + 16 * kt) * 128);
;             f32x4 bb[2][2];
; #pragma unroll
;             for (int jj = 0; jj < 2; ++jj) { const LAS f32x4* bl = bcp + ((MODE == 0) ? (dr0 + t - act0) * 8 : 16 * t + 8 * hf) + bofs[jj];
; #pragma unroll
;                 for (int kt = 0; kt < 2; ++kt) bb[jj][kt] = bl[4 * kt]; }
;             s16x4 vlo[2][4], vhi[2][4];
; #pragma unroll
;             for (int jj = 0; jj < 2; ++jj)
; #pragma unroll
;                 for (int dt = 0; dt < 4; ++dt) { const LAS unsigned char* vp = Sl + vad[jj] + (32 * hf) * 128 + ((dt ^ sv) << 5);
;                     vlo[jj][dt] = __builtin_bit_cast(s16x4, __builtin_amdgcn_ds_read_tr16_b64_v4i16((LAS s16x4*)(vp)));
;                     vhi[jj][dt] = __builtin_bit_cast(s16x4, __builtin_amdgcn_ds_read_tr16_b64_v4i16((LAS s16x4*)(vp + 2048))); }
.LBB0_305:
	s_add_i32 s0, s65, 2
	s_cmp_ge_i32 s0, s23
	s_cselect_b64 s[60:61], -1, 0
	s_cmp_lt_i32 s0, s45
	s_cselect_b64 s[66:67], -1, 0
	s_and_b64 s[60:61], s[60:61], s[66:67]
	s_andn2_b64 vcc, exec, s[60:61]
	s_cbranch_vccnz .LBB0_300
	s_add_i32 s0, s86, s65
	s_add_i32 s0, s0, 2
	s_mul_hi_i32 s14, s0, 0x55555556
	s_lshr_b32 s15, s14, 31
	s_add_i32 s14, s14, s15
	s_mul_i32 s14, s14, 3
	s_sub_i32 s0, s0, s14
	s_lshl_b32 s0, s0, 14
	s_add_i32 s0, s0, 0
	v_add_u32_e32 v2, s0, v89
	v_add_u32_e32 v3, s0, v88
	ds_read_b128 v[130:133], v2
	ds_read_b128 v[134:137], v2 offset:2048
	ds_read_b128 v[138:141], v3
	ds_read_b128 v[142:145], v3 offset:2048
	v_add_u32_e32 v2, s0, v92
	v_add_u32_e32 v3, s0, v91
	ds_read_b128 v[146:149], v2
	ds_read_b128 v[150:153], v2 offset:2048
	ds_read_b128 v[154:157], v3
	ds_read_b128 v[158:161], v3 offset:2048
	v_add_u32_e32 v2, s50, v128
	v_add_u32_e32 v3, 0x10480, v2
	v_add_u32_e32 v2, 0x104c0, v2
	ds_read_b128 v[162:165], v3
	ds_read_b128 v[166:169], v2
	v_add_u32_e32 v2, s50, v127
	v_add_u32_e32 v3, 0x10480, v2
	v_add_u32_e32 v2, 0x104c0, v2
	ds_read_b128 v[170:173], v3
	ds_read_b128 v[174:177], v2
	v_add_u32_e32 v2, s0, v0
	v_add_u32_e32 v3, v2, v94
	v_add_u32_e32 v4, v2, v95
	ds_read_b64_tr_b16 v[78:79], v3 offset:8192
	ds_read_b64_tr_b16 v[80:81], v3 offset:10240
	ds_read_b64_tr_b16 v[74:75], v4 offset:8192
	ds_read_b64_tr_b16 v[76:77], v4 offset:10240
	v_add_u32_e32 v3, v2, v96
	v_add_u32_e32 v2, v2, v97
	ds_read_b64_tr_b16 v[70:71], v3 offset:8192
	ds_read_b64_tr_b16 v[72:73], v3 offset:10240
	ds_read_b64_tr_b16 v[66:67], v2 offset:8192
	ds_read_b64_tr_b16 v[68:69], v2 offset:10240
	v_add_u32_e32 v2, s0, v126
	v_add_u32_e32 v3, v2, v94
	v_add_u32_e32 v4, v2, v95
	ds_read_b64_tr_b16 v[14:15], v3 offset:8192
	ds_read_b64_tr_b16 v[16:17], v3 offset:10240
	ds_read_b64_tr_b16 v[10:11], v4 offset:8192
	ds_read_b64_tr_b16 v[12:13], v4 offset:10240
	v_add_u32_e32 v3, v2, v96
	v_add_u32_e32 v4, v2, v97
	ds_read_b64_tr_b16 v[6:7], v3 offset:8192
	ds_read_b64_tr_b16 v[8:9], v3 offset:10240
	ds_read_b64_tr_b16 v[2:3], v4 offset:8192
	ds_read_b64_tr_b16 v[4:5], v4 offset:10240
	s_waitcnt lgkmcnt(14)
; __device__ __forceinline__ unsigned cvtpk(float lo, float hi) { f32x2 v = {lo, hi}; bf16x2_t b = __builtin_convertvector(v, bf16x2_t); return __builtin_bit_cast(unsigned, b); }
; __device__ __forceinline__ float vmax3(float a, float b, float c) { return __builtin_elementwise_maximum(__builtin_elementwise_maximum(a, b), c); }
; template <int MODE> ...
;     ...
;             f32x4 s[2][2];
; #pragma unroll
;             for (int jj = 0; jj < 2; ++jj)
; #pragma unroll
;                 for (int kt = 0; kt < 2; ++kt) { f32x4 a = (MODE == 0) ? bb[jj][kt] + mneg[jj][kt] : bb[jj][kt];
;                     a = __builtin_amdgcn_mfma_f32_16x16x32_bf16(kf[jj][kt][0], qf[jj][0], a, 0, 0, 0);
;                     s[jj][kt] = __builtin_amdgcn_mfma_f32_16x16x32_bf16(kf[jj][kt][1], qf[jj][1], a, 0, 0, 0); }
;             u32x4 pw[2];
; #pragma unroll
;             for (int jj = 0; jj < 2; ++jj) {
;                 const float tm = vmax3(vmax3(s[jj][0][0], s[jj][0][1], s[jj][0][2]), vmax3(s[jj][0][3], s[jj][1][0], s[jj][1][1]), vmax3(s[jj][1][2], s[jj][1][3], s[jj][1][3]));
;                 const float mn = quad_max3(mrun[jj], tm);
;                 const float alpha = __builtin_amdgcn_exp2f(mrun[jj] - mn);
;                 mrun[jj] = mn;
;                 float rsum = 0.f;
; #pragma unroll
;                 for (int kt = 0; kt < 2; ++kt)
; #pragma unroll
;                     for (int e = 0; e < 4; ++e) { s[jj][kt][e] = __builtin_amdgcn_exp2f(s[jj][kt][e] - mn); rsum += s[jj][kt][e]; }
;                 lrun[jj] = lrun[jj] * alpha + rsum;
; #pragma unroll
;                 for (int dt = 0; dt < 4; ++dt) o[jj][dt] *= alpha;
;                 pw[jj].x = cvtpk(s[jj][0][0], s[jj][0][1]); pw[jj].y = cvtpk(s[jj][0][2], s[jj][0][3]); pw[jj].z = cvtpk(s[jj][1][0], s[jj][1][1]); pw[jj].w = cvtpk(s[jj][1][2], s[jj][1][3]);
;             }
; #pragma unroll
;             for (int jj = 0; jj < 2; ++jj)
; #pragma unroll
;                 for (int dt = 0; dt < 4; ++dt) {
;                     const bf16x8 vf = (bf16x8){vlo[jj][dt][0], vlo[jj][dt][1], vlo[jj][dt][2], vlo[jj][dt][3], vhi[jj][dt][0], vhi[jj][dt][1], vhi[jj][dt][2], vhi[jj][dt][3]};
;                     o[jj][dt] = __builtin_amdgcn_mfma_f32_16x16x32_bf16(vf, __builtin_bit_cast(bf16x8, pw[jj]), o[jj][dt], 0, 0, 0); }
	v_pk_add_f32 v[164:165], v[112:113], v[164:165]
	v_pk_add_f32 v[162:163], v[110:111], v[162:163]
	s_nop 1
	v_mfma_f32_16x16x32_bf16 v[130:133], v[130:133], v[30:33], v[162:165]
	s_nop 2
	v_pk_add_f32 v[164:165], v[114:115], v[168:169]
	v_pk_add_f32 v[162:163], v[108:109], v[166:167]
	v_mfma_f32_16x16x32_bf16 v[130:133], v[138:141], v[26:29], v[130:133]
	v_pk_add_f32 v[140:141], v[106:107], v[172:173]
	v_pk_add_f32 v[138:139], v[102:103], v[170:171]
	v_mfma_f32_16x16x32_bf16 v[134:137], v[134:137], v[30:33], v[162:165]
	v_mfma_f32_16x16x32_bf16 v[134:137], v[142:145], v[26:29], v[134:137]
	s_nop 2
	v_maximum3_f32 v129, v130, v131, v132
	v_pk_add_f32 v[164:165], v[104:105], v[176:177]
	v_pk_add_f32 v[162:163], v[100:101], v[174:175]
	v_mfma_f32_16x16x32_bf16 v[138:141], v[146:149], v[22:25], v[138:141]
	v_mfma_f32_16x16x32_bf16 v[138:141], v[154:157], v[18:21], v[138:141]
	v_maximum3_f32 v142, v133, v134, v135
	v_maximum3_f32 v143, v136, v137, v137
	v_maximum3_f32 v129, v129, v142, v143
	v_mov_b32_e32 v142, v129
	s_nop 1
	v_permlane16_swap_b32_e32 v129, v142
	v_maximum3_f32 v129, v129, v142, v142
	v_mov_b32_e32 v142, v129
	s_nop 1
	v_permlane32_swap_b32_e32 v129, v142
	v_maximum3_f32 v129, v125, v129, v142
	v_mfma_f32_16x16x32_bf16 v[142:145], v[150:153], v[22:25], v[162:165]
	v_sub_f32_e32 v130, v130, v129
	v_exp_f32_e32 v146, v130
	v_sub_f32_e32 v130, v131, v129
	v_exp_f32_e32 v148, v130
	v_sub_f32_e32 v130, v132, v129
	v_mfma_f32_16x16x32_bf16 v[142:145], v[158:161], v[18:21], v[142:145]
	v_exp_f32_e32 v150, v130
	v_sub_f32_e32 v130, v133, v129
	v_exp_f32_e32 v152, v130
	v_sub_f32_e32 v130, v134, v129
	v_sub_f32_e32 v125, v125, v129
	v_exp_f32_e32 v134, v130
	v_sub_f32_e32 v130, v135, v129
	v_exp_f32_e32 v154, v130
	v_sub_f32_e32 v130, v136, v129
	v_exp_f32_e32 v136, v125
	v_sub_f32_e32 v125, v137, v129
	v_exp_f32_e32 v158, v125
	v_maximum3_f32 v125, v138, v139, v140
	v_maximum3_f32 v133, v141, v142, v143
	v_maximum3_f32 v135, v144, v145, v145
	v_maximum3_f32 v125, v125, v133, v135
	v_mov_b32_e32 v133, v125
	s_nop 1
	v_permlane16_swap_b32_e32 v125, v133
	v_maximum3_f32 v125, v125, v133, v133
	v_mov_b32_e32 v133, v125
	s_nop 1
	v_permlane32_swap_b32_e32 v125, v133
	v_maximum3_f32 v160, v124, v125, v133
	v_sub_f32_e32 v125, v138, v160
	v_sub_f32_e32 v135, v140, v160
	v_sub_f32_e32 v138, v143, v160
	v_exp_f32_e32 v156, v130
	v_pk_mul_f32 v[56:57], v[56:57], v[136:137] op_sel_hi:[1,0]
	v_pk_mul_f32 v[54:55], v[54:55], v[136:137] op_sel_hi:[1,0]
	v_pk_mul_f32 v[64:65], v[64:65], v[136:137] op_sel_hi:[1,0]
	v_pk_mul_f32 v[62:63], v[62:63], v[136:137] op_sel_hi:[1,0]
	v_pk_mul_f32 v[60:61], v[60:61], v[136:137] op_sel_hi:[1,0]
	v_pk_mul_f32 v[58:59], v[58:59], v[136:137] op_sel_hi:[1,0]
	v_pk_mul_f32 v[52:53], v[52:53], v[136:137] op_sel_hi:[1,0]
	v_pk_mul_f32 v[50:51], v[50:51], v[136:137] op_sel_hi:[1,0]
	v_sub_f32_e32 v137, v124, v160
	v_exp_f32_e32 v151, v135
	v_sub_f32_e32 v135, v141, v160
	v_exp_f32_e32 v155, v138
	v_sub_f32_e32 v138, v144, v160
	v_exp_f32_e32 v147, v125
	v_sub_f32_e32 v125, v139, v160
	v_exp_f32_e32 v153, v135
	v_sub_f32_e32 v135, v142, v160
	v_exp_f32_e32 v157, v138
	v_sub_f32_e32 v138, v145, v160
	v_exp_f32_e32 v137, v137
	v_exp_f32_e32 v149, v125
	v_exp_f32_e32 v135, v135
	v_exp_f32_e32 v159, v138
	v_cvt_pk_bf16_f32 v130, v146, v148
	v_cvt_pk_bf16_f32 v131, v150, v152
	v_cvt_pk_bf16_f32 v132, v134, v154
	v_cvt_pk_bf16_f32 v133, v156, v158
	v_pk_add_f32 v[124:125], v[146:147], 0 op_sel_hi:[1,0]
	s_waitcnt lgkmcnt(12)
	v_mfma_f32_16x16x32_bf16 v[62:65], v[74:77], v[130:133], v[62:65]
	v_mov_b32_e32 v76, v137
	v_pk_add_f32 v[124:125], v[148:149], v[124:125]
	v_pk_mul_f32 v[48:49], v[48:49], v[76:77] op_sel_hi:[1,0]
	s_waitcnt lgkmcnt(10)
	v_mfma_f32_16x16x32_bf16 v[58:61], v[70:73], v[130:133], v[58:61]
	v_pk_mul_f32 v[46:47], v[46:47], v[76:77] op_sel_hi:[1,0]
	v_cvt_pk_bf16_f32 v70, v147, v149
	v_cvt_pk_bf16_f32 v71, v151, v153
	v_cvt_pk_bf16_f32 v72, v135, v155
	v_cvt_pk_bf16_f32 v73, v157, v159
	v_mfma_f32_16x16x32_bf16 v[54:57], v[78:81], v[130:133], v[54:57]
	v_pk_add_f32 v[78:79], v[150:151], v[124:125]
	v_pk_add_f32 v[78:79], v[152:153], v[78:79]
	s_waitcnt lgkmcnt(6)
	v_mfma_f32_16x16x32_bf16 v[46:49], v[14:17], v[70:73], v[46:49]
	v_pk_mul_f32 v[16:17], v[44:45], v[76:77] op_sel_hi:[1,0]
	v_pk_mul_f32 v[14:15], v[42:43], v[76:77] op_sel_hi:[1,0]
	v_pk_add_f32 v[74:75], v[134:135], v[78:79]
	v_mfma_f32_16x16x32_bf16 v[50:53], v[66:69], v[130:133], v[50:53]
	v_pk_add_f32 v[74:75], v[154:155], v[74:75]
	v_pk_add_f32 v[66:67], v[156:157], v[74:75]
	s_waitcnt lgkmcnt(4)
	v_mfma_f32_16x16x32_bf16 v[42:45], v[10:13], v[70:73], v[14:17]
	v_pk_mul_f32 v[12:13], v[40:41], v[76:77] op_sel_hi:[1,0]
	v_pk_mul_f32 v[10:11], v[38:39], v[76:77] op_sel_hi:[1,0]
	v_pk_add_f32 v[14:15], v[158:159], v[66:67]
	s_waitcnt lgkmcnt(2)
	v_mfma_f32_16x16x32_bf16 v[38:41], v[6:9], v[70:73], v[10:13]
	v_pk_mul_f32 v[8:9], v[36:37], v[76:77] op_sel_hi:[1,0]
	v_pk_mul_f32 v[6:7], v[34:35], v[76:77] op_sel_hi:[1,0]
	v_pk_fma_f32 v[98:99], v[98:99], v[136:137], v[14:15]
	s_waitcnt lgkmcnt(0)
	v_mfma_f32_16x16x32_bf16 v[34:37], v[2:5], v[70:73], v[6:9]
	v_mov_b32_e32 v125, v129
	v_mov_b32_e32 v124, v160
	s_branch .LBB0_300
	s_nop 0
	s_nop 0
	s_nop 0
	s_nop 0
